# second-round W_in transposition items moved from the waves of XCDs 0-3 to those of XCDs 2-5, so the teams that carry the P2 arrival guard have one item per wave
# baseline (speedup 1.0000x reference)
; __host__ __device__ __forceinline__ int tile_slot(int pn) { if (pn >= 16) return pn - 12; const int q = pn & 7; if (q >= 6) return (pn >> 3) * 2 + (q - 6); return (pn >> 3) * 6 + q; }
; #define GAS __attribute__((address_space(1)))
; #define LAS __attribute__((address_space(3)))
; #define LDS_WAIT() asm volatile("s_waitcnt lgkmcnt(0)" ::: "memory")
; __device__ __forceinline__ unsigned pk2(float lo, float hi) { const f32x2_t v = {lo, hi}; return __builtin_bit_cast(unsigned, __builtin_convertvector(v, bf16x2_t)); }
; __device__ __forceinline__ void p0_transpose_item(const float* W, int ldw, int src_col0, int k0, bf16_t* WT, int ldk, int dst_row0, int dst_k0, LAS float* scr, int lane) {
; #pragma unroll
;     for (int i = 0; i < 8; ++i) { const int kk = 8 * i + (lane >> 3), n4 = 4 * (lane & 7);
;         const f32x4 w = *(const GAS f32x4*)(W + (size_t)(k0 + kk) * ldw + src_col0 + n4); LAS float* d = scr + kk * 33 + n4; d[0] = w[0]; d[1] = w[1]; d[2] = w[2]; d[3] = w[3]; }
;     LDS_WAIT(); asm volatile("" ::: "memory");
;     const int c = lane & 7;
; #pragma unroll
;     for (int j = 0; j < 4; ++j) { const int n = (lane >> 3) + 8 * j; const LAS float* s = scr + (8 * c) * 33 + n;
;         v4u o; o.x = pk2(s[0 * 33], s[1 * 33]); o.y = pk2(s[2 * 33], s[3 * 33]); o.z = pk2(s[4 * 33], s[5 * 33]); o.w = pk2(s[6 * 33], s[7 * 33]);
;         *(GAS v4u*)(WT + (size_t)(dst_row0 + n) * ldk + dst_k0 + k0 + 8 * c) = o; }
;     LDS_WAIT(); asm volatile("" ::: "memory");
; }
; __global__ void __launch_bounds__(NWAVES * 64, 2) fwd(Args args) {
;     ...
;         const int gw = vcu * NWAVES + wave, NGW = G * NWAVES;
;         LAS float* scr = (LAS float*)(lds + RING_OFF + wave * 8704);
;         constexpr int I_IN = 16 * 192;
;         for (int it = gw; it < I_IN; it += NGW) { const int kb = it / 192, nb = it % 192, pn = nb >> 3, row = tile_slot(pn) * 256 + (nb & 7) * 32;
;             p0_transpose_item(w_in, PROJW, orig_col(32 * nb), 64 * kb, tile_is_late(pn) ? WING_T : WIN_T, 1024, row, 0, scr, lane); }
.LBB0_17:
	s_or_b64 exec, exec, s[6:7]
	s_add_u32 s84, s60, 0x600000
	s_addc_u32 s5, s61, 0
	s_add_u32 s64, s60, 0xc00000
	s_addc_u32 s65, s61, 0
	s_lshr_b32 s48, s66, 6
	s_load_dwordx16 s[16:31], s[0:1], 0x0
	s_cmp_lt_i32 s56, 1
	s_cselect_b64 s[6:7], -1, 0
	s_cmp_gt_i32 s57, 0
	s_cselect_b64 s[10:11], -1, 0
	s_and_b64 s[6:7], s[6:7], s[10:11]
	s_andn2_b64 vcc, exec, s[6:7]
	v_and_b32_e32 v234, 63, v0
	v_writelane_b32 v240, s48, 2
	s_cbranch_vccnz .LBB0_123
	s_lshl_b32 s3, s8, 3
	s_add_i32 s40, s3, s48
	s_movk_i32 s42, 0x600
	v_lshrrev_b32_e32 v8, 3, v234
	s_cmpk_gt_i32 s40, 0xbff
	v_lshlrev_b32_e32 v9, 3, v0
	v_mov_b32_e32 v3, 0
	v_lshlrev_b32_e32 v34, 2, v8
	s_cbranch_scc1 .LBB0_43
	s_mul_i32 s3, s48, 0x2200
	v_lshlrev_b32_e32 v1, 4, v0
	s_add_i32 s3, s3, 0
	v_and_b32_e32 v2, 0x70, v1
	s_waitcnt lgkmcnt(0)
	v_lshl_add_u64 v[4:5], s[20:21], 0, v[2:3]
	v_add_u32_e32 v15, s3, v2
	v_mul_u32_u24_e32 v16, 0x84, v8
	v_and_b32_e32 v2, 56, v9
	v_mul_u32_u24_e32 v14, 0x84, v2
	v_add_u32_e32 v15, v15, v16
	v_or_b32_e32 v1, 8, v8
	v_or_b32_e32 v6, 16, v8
	v_or_b32_e32 v7, 24, v8
	v_or_b32_e32 v10, 32, v8
	v_or_b32_e32 v11, 40, v8
	v_or_b32_e32 v12, 48, v8
	v_or_b32_e32 v13, 56, v8
	v_add3_u32 v14, s3, v14, v34
	s_lshl_b32 s3, s40, 5
	s_lshl_b32 s4, s42, 5
	s_lshl_b32 s12, s40, 8
	s_lshl_b32 s13, s42, 8
	s_movk_i32 s14, 0x6020
	v_add_u32_e32 v16, 0x420, v15
	v_add_u32_e32 v17, 0x428, v15
	v_add_u32_e32 v18, 0x840, v15
	v_add_u32_e32 v19, 0x848, v15
	v_add_u32_e32 v20, 0xc60, v15
	v_add_u32_e32 v21, 0xc68, v15
	v_add_u32_e32 v22, 0x1080, v15
	v_add_u32_e32 v23, 0x1088, v15
	v_add_u32_e32 v24, 0x14a0, v15
	v_add_u32_e32 v25, 0x14a8, v15
	v_add_u32_e32 v26, 0x18c0, v15
	v_add_u32_e32 v27, 0x18c8, v15
	v_add_u32_e32 v28, 0x1ce0, v15
	v_add_u32_e32 v29, 0x1ce8, v15
	v_lshlrev_b32_e32 v2, 1, v2
	s_mov_b32 s15, s40
	s_branch .LBB0_21
.LBB0_20:
	s_lshl_b32 s8, s35, 8
	s_and_b32 s9, s36, 0xe0
	s_or_b32 s35, s8, s9
	s_lshl_b32 s8, s11, 6
	s_and_b32 s9, s33, 48
	s_cmp_eq_u32 s9, 48
	s_cselect_b64 s[36:37], -1, 0
	s_or_b64 s[6:7], s[6:7], s[36:37]
	s_and_b64 s[6:7], s[6:7], exec
	s_cselect_b32 s33, s5, s65
	s_cselect_b32 s36, s84, s64
	s_ashr_i32 s11, s10, 31
	v_lshl_add_u64 v[60:61], s[10:11], 2, v[4:5]
	v_or_b32_e32 v35, s8, v6
	v_mad_i64_i32 v[40:41], s[6:7], v35, s14, v[60:61]
	v_or_b32_e32 v35, s8, v7
	v_mad_i64_i32 v[44:45], s[6:7], v35, s14, v[60:61]
	v_or_b32_e32 v35, s8, v10
	v_or_b32_e32 v30, s8, v8
	v_or_b32_e32 v32, s8, v1
	v_mad_i64_i32 v[48:49], s[6:7], v35, s14, v[60:61]
	v_or_b32_e32 v35, s8, v11
	v_mad_i64_i32 v[30:31], s[6:7], v30, s14, v[60:61]
	v_mad_i64_i32 v[36:37], s[6:7], v32, s14, v[60:61]
	v_mad_i64_i32 v[52:53], s[6:7], v35, s14, v[60:61]
	global_load_dwordx4 v[30:33], v[30:31], off nt
	s_nop 0
	global_load_dwordx4 v[36:39], v[36:37], off nt
	s_nop 0
	global_load_dwordx4 v[40:43], v[40:41], off nt
	s_nop 0
	global_load_dwordx4 v[44:47], v[44:45], off nt
	s_nop 0
	global_load_dwordx4 v[48:51], v[48:49], off nt
	s_nop 0
	global_load_dwordx4 v[52:55], v[52:53], off nt
	v_or_b32_e32 v35, s8, v12
	v_mad_i64_i32 v[56:57], s[6:7], v35, s14, v[60:61]
	global_load_dwordx4 v[56:59], v[56:57], off nt
	v_or_b32_e32 v35, s8, v13
	v_mad_i64_i32 v[60:61], s[6:7], v35, s14, v[60:61]
	global_load_dwordx4 v[60:63], v[60:61], off nt
	s_ashr_i32 s9, s8, 31
	s_lshl_b64 s[6:7], s[8:9], 1
	v_or_b32_e32 v64, s35, v8
	s_add_u32 s6, s36, s6
	v_ashrrev_i32_e32 v65, 31, v64
	s_addc_u32 s7, s33, s7
	v_lshlrev_b64 v[64:65], 11, v[64:65]
	v_lshl_add_u64 v[68:69], s[6:7], 0, v[2:3]
	v_or_b32_e32 v66, s35, v1
	v_lshl_add_u64 v[64:65], v[68:69], 0, v[64:65]
	v_ashrrev_i32_e32 v67, 31, v66
	v_lshlrev_b64 v[66:67], 11, v[66:67]
	v_lshl_add_u64 v[66:67], v[68:69], 0, v[66:67]
	s_add_i32 s15, s15, s42
	s_add_i32 s3, s3, s4
	s_add_i32 s12, s12, s13
	s_sub_i32 s100, s15, 0x800
	s_cmpk_gt_u32 s100, 0x3ff
	s_waitcnt vmcnt(7)
	ds_write2_b32 v15, v30, v31 offset1:1
	ds_write2_b32 v15, v32, v33 offset0:2 offset1:3
	s_waitcnt vmcnt(6)
	ds_write2_b32 v16, v36, v37 offset1:1
	ds_write2_b32 v17, v38, v39 offset1:1
	s_waitcnt vmcnt(5)
	ds_write2_b32 v18, v40, v41 offset1:1
	ds_write2_b32 v19, v42, v43 offset1:1
	s_waitcnt vmcnt(4)
	ds_write2_b32 v20, v44, v45 offset1:1
	ds_write2_b32 v21, v46, v47 offset1:1
	s_waitcnt vmcnt(3)
	ds_write2_b32 v22, v48, v49 offset1:1
	ds_write2_b32 v23, v50, v51 offset1:1
	s_waitcnt vmcnt(2)
	ds_write2_b32 v24, v52, v53 offset1:1
	ds_write2_b32 v25, v54, v55 offset1:1
	s_waitcnt vmcnt(1)
	ds_write2_b32 v26, v56, v57 offset1:1
	ds_write2_b32 v27, v58, v59 offset1:1
	s_waitcnt vmcnt(0)
	ds_write2_b32 v28, v60, v61 offset1:1
	ds_write2_b32 v29, v62, v63 offset1:1
	s_waitcnt lgkmcnt(0)
	ds_read2_b32 v[32:33], v14 offset0:33 offset1:41
	ds_read2_b32 v[36:37], v14 offset1:8
	ds_read2_b32 v[38:39], v14 offset0:66 offset1:74
	ds_read2_b32 v[40:41], v14 offset0:99 offset1:107
	ds_read2_b32 v[42:43], v14 offset0:132 offset1:140
	ds_read2_b32 v[44:45], v14 offset0:165 offset1:173
	ds_read2_b32 v[46:47], v14 offset0:198 offset1:206
	ds_read2_b32 v[48:49], v14 offset0:231 offset1:239
	ds_read2_b32 v[50:51], v14 offset0:49 offset1:57
	ds_read2_b32 v[52:53], v14 offset0:16 offset1:24
	ds_read2_b32 v[54:55], v14 offset0:82 offset1:90
	ds_read2_b32 v[56:57], v14 offset0:115 offset1:123
	ds_read2_b32 v[58:59], v14 offset0:148 offset1:156
	ds_read2_b32 v[60:61], v14 offset0:181 offset1:189
	s_waitcnt lgkmcnt(12)
	v_cvt_pk_bf16_f32 v30, v36, v32
	s_waitcnt lgkmcnt(10)
	v_cvt_pk_bf16_f32 v31, v38, v40
	v_cvt_pk_bf16_f32 v36, v37, v33
	s_waitcnt lgkmcnt(8)
	v_cvt_pk_bf16_f32 v32, v42, v44
	s_waitcnt lgkmcnt(6)
	v_cvt_pk_bf16_f32 v33, v46, v48
	global_store_dwordx4 v[64:65], v[30:33], off sc1
	v_cvt_pk_bf16_f32 v37, v39, v41
	v_cvt_pk_bf16_f32 v38, v43, v45
	ds_read2_b32 v[40:41], v14 offset0:214 offset1:222
	ds_read2_b32 v[42:43], v14 offset0:247 offset1:255
	v_cvt_pk_bf16_f32 v39, v47, v49
	global_store_dwordx4 v[66:67], v[36:39], off sc1
	s_waitcnt lgkmcnt(6)
	v_cvt_pk_bf16_f32 v30, v52, v50
	s_waitcnt lgkmcnt(4)
	v_cvt_pk_bf16_f32 v31, v54, v56
	v_or_b32_e32 v36, s35, v6
	v_ashrrev_i32_e32 v37, 31, v36
	v_lshlrev_b64 v[36:37], 11, v[36:37]
	s_waitcnt lgkmcnt(2)
	v_cvt_pk_bf16_f32 v32, v58, v60
	s_waitcnt lgkmcnt(0)
	v_cvt_pk_bf16_f32 v33, v40, v42
	v_lshl_add_u64 v[36:37], v[68:69], 0, v[36:37]
	global_store_dwordx4 v[36:37], v[30:33], off sc1
	v_or_b32_e32 v36, s35, v7
	v_ashrrev_i32_e32 v37, 31, v36
	v_lshlrev_b64 v[36:37], 11, v[36:37]
	v_cvt_pk_bf16_f32 v30, v53, v51
	v_cvt_pk_bf16_f32 v31, v55, v57
	v_cvt_pk_bf16_f32 v32, v59, v61
	v_cvt_pk_bf16_f32 v33, v41, v43
	v_lshl_add_u64 v[36:37], v[68:69], 0, v[36:37]
	global_store_dwordx4 v[36:37], v[30:33], off sc1
	s_waitcnt lgkmcnt(0)
	s_cbranch_scc1 .LBB0_43
